# v37 + ssm_a: WA ring-prologue loads of both halves issued before the U-stage waits and barrier
# speedup vs baseline: 1.0060x; 1.0060x over previous
; #define LAS __attribute__((address_space(3)))
; __device__ __forceinline__ void ssm_stage_u(unsigned char* ws, LAS unsigned char* lds, int g, int cb, int hh, int tid) {
;     asm volatile("" : "+v"(tid));
;     const bf16* U = (const bf16*)(ws + AR_U);
;     u32x4 v[8];
; #pragma unroll
;     for (int r = 0; r < 8; ++r) { const int c = r * 512 + tid, jj = c >> 7, col = (c >> 1) & 63, part = c & 1;
;         v[r] = *(const u32x4*)(U + ((size_t)((cb * 64 + col) * 64 + hh * 32 + jj) * 512 + g * 16 + part * 8)); }
; #pragma unroll
;     for (int r = 0; r < 8; ++r) { const int c = r * 512 + tid; *(LAS u32x4*)(lds + SS_UB + c * 16) = v[r]; }
; }
; __device__ __forceinline__ void ssm_a_task(unsigned char* ws, LAS unsigned char* lds, int task, int tid) {
;     const int lane = tid & 63, wid = tid >> 6, rr = lane & 15, kk = lane >> 4;
;     const int g = task >> 3, cb = task & 7;
;     f32x4 acc[2][4];
; #pragma unroll
;     for (int a = 0; a < 2; ++a)
; #pragma unroll
;         for (int c = 0; c < 4; ++c) acc[a][c] = (f32x4){0.f, 0.f, 0.f, 0.f};
;     const bf16* WA = (const bf16*)(ws + WS_WA) + ((size_t)(g * 256 + wid * 32 + rr) * 1024 + 8 * kk);
;     for (int hh = 0; hh < 2; ++hh) {
;         ssm_stage_u(ws, lds, g, cb, hh, tid);
;         __syncthreads();
; #pragma unroll 4
;         for (int ks = 0; ks < 16; ++ks) {
;             bf16x8 bfr[4], afr[2];
; #pragma unroll
;             for (int a = 0; a < 2; ++a) afr[a] = *(const bf16x8*)(WA + (size_t)a * 16 * 1024 + (hh * 16 + ks) * 32);
.LBB0_603:
	s_ashr_i32 s16, s54, 3
	v_mov_b32_e32 v30, v44
	s_and_b32 s17, s54, 7
	s_lshl_b32 s14, s16, 4
	s_lshl_b32 s3, s17, 12
	v_lshlrev_b32_e32 v0, 5, v30
	s_ashr_i32 s15, s14, 31
	v_and_b32_e32 v0, 0xfc0, v0
	s_lshl_b64 s[14:15], s[14:15], 1
	v_or_b32_e32 v31, s3, v0
	v_ashrrev_i32_e32 v0, 7, v30
	v_add_u32_e32 v4, 0x200, v30
	s_add_u32 s34, s4, s14
	s_waitcnt vmcnt(1)
	v_lshlrev_b32_e32 v38, 4, v30
	v_add_u32_e32 v0, v31, v0
	v_ashrrev_i32_e32 v4, 7, v4
	v_add_u32_e32 v8, 0x400, v30
	s_addc_u32 s35, s5, s15
	v_and_b32_e32 v184, 16, v38
	v_ashrrev_i32_e32 v1, 31, v0
	v_add_u32_e32 v4, v31, v4
	v_ashrrev_i32_e32 v8, 7, v8
	v_add_u32_e32 v12, 0x600, v30
	v_lshl_add_u64 v[28:29], s[34:35], 0, v[184:185]
	v_lshlrev_b64 v[0:1], 10, v[0:1]
	v_ashrrev_i32_e32 v5, 31, v4
	v_add_u32_e32 v8, v31, v8
	v_ashrrev_i32_e32 v12, 7, v12
	v_add_u32_e32 v16, 0x800, v30
	v_lshl_add_u64 v[0:1], v[28:29], 0, v[0:1]
	v_lshlrev_b64 v[4:5], 10, v[4:5]
	v_ashrrev_i32_e32 v9, 31, v8
	v_add_u32_e32 v12, v31, v12
	v_ashrrev_i32_e32 v16, 7, v16
	v_add_u32_e32 v20, 0xa00, v30
	global_load_dwordx4 v[0:3], v[0:1], off
	v_lshl_add_u64 v[4:5], v[28:29], 0, v[4:5]
	v_lshlrev_b64 v[8:9], 10, v[8:9]
	v_ashrrev_i32_e32 v13, 31, v12
	v_add_u32_e32 v16, v31, v16
	v_ashrrev_i32_e32 v20, 7, v20
	v_add_u32_e32 v24, 0xc00, v30
	global_load_dwordx4 v[4:7], v[4:5], off
	v_lshl_add_u64 v[8:9], v[28:29], 0, v[8:9]
	v_lshlrev_b64 v[12:13], 10, v[12:13]
	v_ashrrev_i32_e32 v17, 31, v16
	v_add_u32_e32 v20, v31, v20
	v_ashrrev_i32_e32 v24, 7, v24
	v_add_u32_e32 v30, 0xe00, v30
	global_load_dwordx4 v[8:11], v[8:9], off
	v_lshl_add_u64 v[12:13], v[28:29], 0, v[12:13]
	v_lshlrev_b64 v[16:17], 10, v[16:17]
	v_ashrrev_i32_e32 v21, 31, v20
	v_add_u32_e32 v24, v31, v24
	v_ashrrev_i32_e32 v30, 7, v30
	global_load_dwordx4 v[12:15], v[12:13], off
	v_lshl_add_u64 v[16:17], v[28:29], 0, v[16:17]
	v_lshlrev_b64 v[20:21], 10, v[20:21]
	v_ashrrev_i32_e32 v25, 31, v24
	v_add_u32_e32 v30, v31, v30
	global_load_dwordx4 v[16:19], v[16:17], off
	v_lshl_add_u64 v[20:21], v[28:29], 0, v[20:21]
	v_lshlrev_b64 v[24:25], 10, v[24:25]
	v_ashrrev_i32_e32 v31, 31, v30
	global_load_dwordx4 v[20:23], v[20:21], off
	v_lshl_add_u64 v[24:25], v[28:29], 0, v[24:25]
	v_lshlrev_b64 v[30:31], 10, v[30:31]
	global_load_dwordx4 v[24:27], v[24:25], off
	v_lshl_add_u64 v[28:29], v[28:29], 0, v[30:31]
	global_load_dwordx4 v[28:31], v[28:29], off
	v_add_u32_e32 v38, 0, v38
	v_add_u32_e32 v38, 0x10000, v38
	s_mov_b32 s12, 0
	v_lshl_add_u32 v132, s16, 8, v46
	v_ashrrev_i32_e32 v133, 31, v132
	v_lshlrev_b64 v[132:133], 11, v[132:133]
	v_lshl_add_u64 v[40:41], v[34:35], 0, v[132:133]
	v_add_co_u32_e32 v164, vcc, 0xffff8000, v40
	s_nop 1
	v_addc_co_u32_e32 v165, vcc, -1, v41, vcc
	global_load_dwordx4 v[100:103], v[40:41], off offset:-192
	global_load_dwordx4 v[104:107], v[164:165], off offset:-192
	global_load_dwordx4 v[108:111], v[40:41], off offset:-128
	global_load_dwordx4 v[112:115], v[164:165], off offset:-128
	global_load_dwordx4 v[116:119], v[40:41], off offset:-64
	global_load_dwordx4 v[120:123], v[164:165], off offset:-64
	global_load_dwordx4 v[124:127], v[40:41], off offset:0
	global_load_dwordx4 v[128:131], v[164:165], off offset:0
	s_waitcnt vmcnt(15)
	ds_write_b128 v38, v[0:3]
	s_waitcnt vmcnt(14)
	ds_write_b128 v38, v[4:7] offset:8192
	s_waitcnt vmcnt(13)
	ds_write_b128 v38, v[8:11] offset:16384
	s_waitcnt vmcnt(12)
	ds_write_b128 v38, v[12:15] offset:24576
	s_waitcnt vmcnt(11)
	ds_write_b128 v38, v[16:19] offset:32768
	s_waitcnt vmcnt(10)
	ds_write_b128 v38, v[20:23] offset:40960
	s_waitcnt vmcnt(9)
	ds_write_b128 v38, v[24:27] offset:49152
	s_waitcnt vmcnt(8)
	ds_write_b128 v38, v[28:31] offset:57344
	v_lshl_add_u32 v0, s16, 8, v46
	v_ashrrev_i32_e32 v1, 31, v0
	v_lshlrev_b64 v[38:39], 11, v[0:1]
	v_mov_b32_e32 v0, 0
	v_lshl_add_u64 v[40:41], v[34:35], 0, v[38:39]
	v_mov_b32_e32 v1, v0
	v_mov_b32_e32 v2, v0
	v_mov_b32_e32 v3, v0
	v_mov_b32_e32 v4, v0
	v_mov_b32_e32 v5, v0
	v_mov_b32_e32 v6, v0
	v_mov_b32_e32 v7, v0
	v_mov_b32_e32 v8, v0
	v_mov_b32_e32 v9, v0
	v_mov_b32_e32 v10, v0
	v_mov_b32_e32 v11, v0
	v_mov_b32_e32 v12, v0
	v_mov_b32_e32 v13, v0
	v_mov_b32_e32 v14, v0
	v_mov_b32_e32 v15, v0
	v_mov_b32_e32 v16, v0
	v_mov_b32_e32 v17, v0
	v_mov_b32_e32 v18, v0
	v_mov_b32_e32 v19, v0
	v_mov_b32_e32 v20, v0
	v_mov_b32_e32 v21, v0
	v_mov_b32_e32 v22, v0
	v_mov_b32_e32 v23, v0
	v_mov_b32_e32 v24, v0
	v_mov_b32_e32 v25, v0
	v_mov_b32_e32 v26, v0
	v_mov_b32_e32 v27, v0
	v_mov_b32_e32 v28, v0
	v_mov_b32_e32 v29, v0
	v_mov_b32_e32 v30, v0
	v_mov_b32_e32 v31, v0
	s_waitcnt lgkmcnt(0)
	s_barrier
; #define LAS __attribute__((address_space(3)))
; __device__ __forceinline__ void ssm_a_task(unsigned char* ws, LAS unsigned char* lds, int task, int tid) {
;     ...
; #pragma unroll 4
;         for (int ks = 0; ks < 16; ++ks) {
;             bf16x8 bfr[4], afr[2];
; #pragma unroll
;             for (int a = 0; a < 2; ++a) afr[a] = *(const bf16x8*)(WA + (size_t)a * 16 * 1024 + (hh * 16 + ks) * 32);
; #pragma unroll
;             for (int c = 0; c < 4; ++c) bfr[c] = *(const LAS bf16x8*)(lds + SS_UB + (((2 * ks + (kk >> 1)) * 64 + c * 16 + rr) * 32 + (kk & 1) * 16));
; #pragma unroll
;             for (int a = 0; a < 2; ++a)
; #pragma unroll
;                 for (int c = 0; c < 4; ++c) acc[a][c] = __builtin_amdgcn_mfma_f32_16x16x32_bf16(afr[a], bfr[c], acc[a][c], 0, 0, 0);
;         }
.LBB0_604:
	v_add_u32_e32 v166, 0x10000, v47
	ds_read_b128 v[132:135], v166 offset:0
	ds_read_b128 v[136:139], v166 offset:512
	ds_read_b128 v[140:143], v166 offset:1024
	ds_read_b128 v[144:147], v166 offset:1536
	ds_read_b128 v[148:151], v166 offset:4096
	ds_read_b128 v[152:155], v166 offset:4608
	ds_read_b128 v[156:159], v166 offset:5120
	ds_read_b128 v[160:163], v166 offset:5632
	s_waitcnt lgkmcnt(4)
	s_waitcnt vmcnt(7)
	v_mfma_f32_16x16x32_bf16 v[12:15], v[100:103], v[132:135], v[12:15]
	v_mfma_f32_16x16x32_bf16 v[8:11], v[100:103], v[136:139], v[8:11]
	v_mfma_f32_16x16x32_bf16 v[4:7], v[100:103], v[140:143], v[4:7]
	v_mfma_f32_16x16x32_bf16 v[0:3], v[100:103], v[144:147], v[0:3]
	s_waitcnt vmcnt(6)
	v_mfma_f32_16x16x32_bf16 v[28:31], v[104:107], v[132:135], v[28:31]
	v_mfma_f32_16x16x32_bf16 v[24:27], v[104:107], v[136:139], v[24:27]
	v_mfma_f32_16x16x32_bf16 v[20:23], v[104:107], v[140:143], v[20:23]
	v_mfma_f32_16x16x32_bf16 v[16:19], v[104:107], v[144:147], v[16:19]
	global_load_dwordx4 v[100:103], v[40:41], off offset:64
	global_load_dwordx4 v[104:107], v[164:165], off offset:64
	ds_read_b128 v[132:135], v166 offset:8192
	ds_read_b128 v[136:139], v166 offset:8704
	ds_read_b128 v[140:143], v166 offset:9216
	ds_read_b128 v[144:147], v166 offset:9728
	s_waitcnt lgkmcnt(4)
	s_waitcnt vmcnt(7)
	v_mfma_f32_16x16x32_bf16 v[12:15], v[108:111], v[148:151], v[12:15]
	v_mfma_f32_16x16x32_bf16 v[8:11], v[108:111], v[152:155], v[8:11]
	v_mfma_f32_16x16x32_bf16 v[4:7], v[108:111], v[156:159], v[4:7]
	v_mfma_f32_16x16x32_bf16 v[0:3], v[108:111], v[160:163], v[0:3]
	s_waitcnt vmcnt(6)
	v_mfma_f32_16x16x32_bf16 v[28:31], v[112:115], v[148:151], v[28:31]
	v_mfma_f32_16x16x32_bf16 v[24:27], v[112:115], v[152:155], v[24:27]
	v_mfma_f32_16x16x32_bf16 v[20:23], v[112:115], v[156:159], v[20:23]
	v_mfma_f32_16x16x32_bf16 v[16:19], v[112:115], v[160:163], v[16:19]
	global_load_dwordx4 v[108:111], v[40:41], off offset:128
	global_load_dwordx4 v[112:115], v[164:165], off offset:128
	ds_read_b128 v[148:151], v166 offset:12288
	ds_read_b128 v[152:155], v166 offset:12800
	ds_read_b128 v[156:159], v166 offset:13312
	ds_read_b128 v[160:163], v166 offset:13824
	s_waitcnt lgkmcnt(4)
	s_waitcnt vmcnt(7)
	v_mfma_f32_16x16x32_bf16 v[12:15], v[116:119], v[132:135], v[12:15]
	v_mfma_f32_16x16x32_bf16 v[8:11], v[116:119], v[136:139], v[8:11]
	v_mfma_f32_16x16x32_bf16 v[4:7], v[116:119], v[140:143], v[4:7]
	v_mfma_f32_16x16x32_bf16 v[0:3], v[116:119], v[144:147], v[0:3]
	s_waitcnt vmcnt(6)
	v_mfma_f32_16x16x32_bf16 v[28:31], v[120:123], v[132:135], v[28:31]
	v_mfma_f32_16x16x32_bf16 v[24:27], v[120:123], v[136:139], v[24:27]
	v_mfma_f32_16x16x32_bf16 v[20:23], v[120:123], v[140:143], v[20:23]
	v_mfma_f32_16x16x32_bf16 v[16:19], v[120:123], v[144:147], v[16:19]
	global_load_dwordx4 v[116:119], v[40:41], off offset:192
	global_load_dwordx4 v[120:123], v[164:165], off offset:192
	ds_read_b128 v[132:135], v166 offset:16384
	ds_read_b128 v[136:139], v166 offset:16896
	ds_read_b128 v[140:143], v166 offset:17408
	ds_read_b128 v[144:147], v166 offset:17920
	s_waitcnt lgkmcnt(4)
	s_waitcnt vmcnt(7)
	v_mfma_f32_16x16x32_bf16 v[12:15], v[124:127], v[148:151], v[12:15]
	v_mfma_f32_16x16x32_bf16 v[8:11], v[124:127], v[152:155], v[8:11]
	v_mfma_f32_16x16x32_bf16 v[4:7], v[124:127], v[156:159], v[4:7]
	v_mfma_f32_16x16x32_bf16 v[0:3], v[124:127], v[160:163], v[0:3]
	s_waitcnt vmcnt(6)
	v_mfma_f32_16x16x32_bf16 v[28:31], v[128:131], v[148:151], v[28:31]
	v_mfma_f32_16x16x32_bf16 v[24:27], v[128:131], v[152:155], v[24:27]
	v_mfma_f32_16x16x32_bf16 v[20:23], v[128:131], v[156:159], v[20:23]
	v_mfma_f32_16x16x32_bf16 v[16:19], v[128:131], v[160:163], v[16:19]
	global_load_dwordx4 v[124:127], v[40:41], off offset:256
	global_load_dwordx4 v[128:131], v[164:165], off offset:256
	ds_read_b128 v[148:151], v166 offset:20480
	ds_read_b128 v[152:155], v166 offset:20992
	ds_read_b128 v[156:159], v166 offset:21504
	ds_read_b128 v[160:163], v166 offset:22016
	s_waitcnt lgkmcnt(4)
	s_waitcnt vmcnt(7)
	v_mfma_f32_16x16x32_bf16 v[12:15], v[100:103], v[132:135], v[12:15]
	v_mfma_f32_16x16x32_bf16 v[8:11], v[100:103], v[136:139], v[8:11]
	v_mfma_f32_16x16x32_bf16 v[4:7], v[100:103], v[140:143], v[4:7]
	v_mfma_f32_16x16x32_bf16 v[0:3], v[100:103], v[144:147], v[0:3]
	s_waitcnt vmcnt(6)
	v_mfma_f32_16x16x32_bf16 v[28:31], v[104:107], v[132:135], v[28:31]
	v_mfma_f32_16x16x32_bf16 v[24:27], v[104:107], v[136:139], v[24:27]
	v_mfma_f32_16x16x32_bf16 v[20:23], v[104:107], v[140:143], v[20:23]
	v_mfma_f32_16x16x32_bf16 v[16:19], v[104:107], v[144:147], v[16:19]
	global_load_dwordx4 v[100:103], v[40:41], off offset:320
	global_load_dwordx4 v[104:107], v[164:165], off offset:320
	ds_read_b128 v[132:135], v166 offset:24576
	ds_read_b128 v[136:139], v166 offset:25088
	ds_read_b128 v[140:143], v166 offset:25600
	ds_read_b128 v[144:147], v166 offset:26112
	s_waitcnt lgkmcnt(4)
	s_waitcnt vmcnt(7)
	v_mfma_f32_16x16x32_bf16 v[12:15], v[108:111], v[148:151], v[12:15]
	v_mfma_f32_16x16x32_bf16 v[8:11], v[108:111], v[152:155], v[8:11]
	v_mfma_f32_16x16x32_bf16 v[4:7], v[108:111], v[156:159], v[4:7]
	v_mfma_f32_16x16x32_bf16 v[0:3], v[108:111], v[160:163], v[0:3]
	s_waitcnt vmcnt(6)
	v_mfma_f32_16x16x32_bf16 v[28:31], v[112:115], v[148:151], v[28:31]
	v_mfma_f32_16x16x32_bf16 v[24:27], v[112:115], v[152:155], v[24:27]
	v_mfma_f32_16x16x32_bf16 v[20:23], v[112:115], v[156:159], v[20:23]
	v_mfma_f32_16x16x32_bf16 v[16:19], v[112:115], v[160:163], v[16:19]
	global_load_dwordx4 v[108:111], v[40:41], off offset:384
	global_load_dwordx4 v[112:115], v[164:165], off offset:384
	ds_read_b128 v[148:151], v166 offset:28672
	ds_read_b128 v[152:155], v166 offset:29184
	ds_read_b128 v[156:159], v166 offset:29696
	ds_read_b128 v[160:163], v166 offset:30208
	s_waitcnt lgkmcnt(4)
; #define LAS __attribute__((address_space(3)))
; __device__ __forceinline__ void ssm_a_task(unsigned char* ws, LAS unsigned char* lds, int task, int tid) {
;     ...
; #pragma unroll 4
;         for (int ks = 0; ks < 16; ++ks) {
;             bf16x8 bfr[4], afr[2];
; #pragma unroll
;             for (int a = 0; a < 2; ++a) afr[a] = *(const bf16x8*)(WA + (size_t)a * 16 * 1024 + (hh * 16 + ks) * 32);
; #pragma unroll
;             for (int c = 0; c < 4; ++c) bfr[c] = *(const LAS bf16x8*)(lds + SS_UB + (((2 * ks + (kk >> 1)) * 64 + c * 16 + rr) * 32 + (kk & 1) * 16));
; #pragma unroll
;             for (int a = 0; a < 2; ++a)
; #pragma unroll
;                 for (int c = 0; c < 4; ++c) acc[a][c] = __builtin_amdgcn_mfma_f32_16x16x32_bf16(afr[a], bfr[c], acc[a][c], 0, 0, 0);
;         }
	s_waitcnt vmcnt(7)
	v_mfma_f32_16x16x32_bf16 v[12:15], v[116:119], v[132:135], v[12:15]
	v_mfma_f32_16x16x32_bf16 v[8:11], v[116:119], v[136:139], v[8:11]
	v_mfma_f32_16x16x32_bf16 v[4:7], v[116:119], v[140:143], v[4:7]
	v_mfma_f32_16x16x32_bf16 v[0:3], v[116:119], v[144:147], v[0:3]
	s_waitcnt vmcnt(6)
	v_mfma_f32_16x16x32_bf16 v[28:31], v[120:123], v[132:135], v[28:31]
	v_mfma_f32_16x16x32_bf16 v[24:27], v[120:123], v[136:139], v[24:27]
	v_mfma_f32_16x16x32_bf16 v[20:23], v[120:123], v[140:143], v[20:23]
	v_mfma_f32_16x16x32_bf16 v[16:19], v[120:123], v[144:147], v[16:19]
	global_load_dwordx4 v[116:119], v[40:41], off offset:448
	global_load_dwordx4 v[120:123], v[164:165], off offset:448
	ds_read_b128 v[132:135], v166 offset:32768
	ds_read_b128 v[136:139], v166 offset:33280
	ds_read_b128 v[140:143], v166 offset:33792
	ds_read_b128 v[144:147], v166 offset:34304
	s_waitcnt lgkmcnt(4)
	s_waitcnt vmcnt(7)
	v_mfma_f32_16x16x32_bf16 v[12:15], v[124:127], v[148:151], v[12:15]
	v_mfma_f32_16x16x32_bf16 v[8:11], v[124:127], v[152:155], v[8:11]
	v_mfma_f32_16x16x32_bf16 v[4:7], v[124:127], v[156:159], v[4:7]
	v_mfma_f32_16x16x32_bf16 v[0:3], v[124:127], v[160:163], v[0:3]
	s_waitcnt vmcnt(6)
	v_mfma_f32_16x16x32_bf16 v[28:31], v[128:131], v[148:151], v[28:31]
	v_mfma_f32_16x16x32_bf16 v[24:27], v[128:131], v[152:155], v[24:27]
	v_mfma_f32_16x16x32_bf16 v[20:23], v[128:131], v[156:159], v[20:23]
	v_mfma_f32_16x16x32_bf16 v[16:19], v[128:131], v[160:163], v[16:19]
	global_load_dwordx4 v[124:127], v[40:41], off offset:512
	global_load_dwordx4 v[128:131], v[164:165], off offset:512
	ds_read_b128 v[148:151], v166 offset:36864
	ds_read_b128 v[152:155], v166 offset:37376
	ds_read_b128 v[156:159], v166 offset:37888
	ds_read_b128 v[160:163], v166 offset:38400
	s_waitcnt lgkmcnt(4)
	s_waitcnt vmcnt(7)
	v_mfma_f32_16x16x32_bf16 v[12:15], v[100:103], v[132:135], v[12:15]
	v_mfma_f32_16x16x32_bf16 v[8:11], v[100:103], v[136:139], v[8:11]
	v_mfma_f32_16x16x32_bf16 v[4:7], v[100:103], v[140:143], v[4:7]
	v_mfma_f32_16x16x32_bf16 v[0:3], v[100:103], v[144:147], v[0:3]
	s_waitcnt vmcnt(6)
	v_mfma_f32_16x16x32_bf16 v[28:31], v[104:107], v[132:135], v[28:31]
	v_mfma_f32_16x16x32_bf16 v[24:27], v[104:107], v[136:139], v[24:27]
	v_mfma_f32_16x16x32_bf16 v[20:23], v[104:107], v[140:143], v[20:23]
	v_mfma_f32_16x16x32_bf16 v[16:19], v[104:107], v[144:147], v[16:19]
	global_load_dwordx4 v[100:103], v[40:41], off offset:576
	global_load_dwordx4 v[104:107], v[164:165], off offset:576
	ds_read_b128 v[132:135], v166 offset:40960
	ds_read_b128 v[136:139], v166 offset:41472
	ds_read_b128 v[140:143], v166 offset:41984
	ds_read_b128 v[144:147], v166 offset:42496
	s_waitcnt lgkmcnt(4)
	s_waitcnt vmcnt(7)
	v_mfma_f32_16x16x32_bf16 v[12:15], v[108:111], v[148:151], v[12:15]
	v_mfma_f32_16x16x32_bf16 v[8:11], v[108:111], v[152:155], v[8:11]
	v_mfma_f32_16x16x32_bf16 v[4:7], v[108:111], v[156:159], v[4:7]
	v_mfma_f32_16x16x32_bf16 v[0:3], v[108:111], v[160:163], v[0:3]
	s_waitcnt vmcnt(6)
	v_mfma_f32_16x16x32_bf16 v[28:31], v[112:115], v[148:151], v[28:31]
	v_mfma_f32_16x16x32_bf16 v[24:27], v[112:115], v[152:155], v[24:27]
	v_mfma_f32_16x16x32_bf16 v[20:23], v[112:115], v[156:159], v[20:23]
	v_mfma_f32_16x16x32_bf16 v[16:19], v[112:115], v[160:163], v[16:19]
	global_load_dwordx4 v[108:111], v[40:41], off offset:640
	global_load_dwordx4 v[112:115], v[164:165], off offset:640
	ds_read_b128 v[148:151], v166 offset:45056
	ds_read_b128 v[152:155], v166 offset:45568
	ds_read_b128 v[156:159], v166 offset:46080
	ds_read_b128 v[160:163], v166 offset:46592
	s_waitcnt lgkmcnt(4)
	s_waitcnt vmcnt(7)
	v_mfma_f32_16x16x32_bf16 v[12:15], v[116:119], v[132:135], v[12:15]
	v_mfma_f32_16x16x32_bf16 v[8:11], v[116:119], v[136:139], v[8:11]
	v_mfma_f32_16x16x32_bf16 v[4:7], v[116:119], v[140:143], v[4:7]
	v_mfma_f32_16x16x32_bf16 v[0:3], v[116:119], v[144:147], v[0:3]
	s_waitcnt vmcnt(6)
	v_mfma_f32_16x16x32_bf16 v[28:31], v[120:123], v[132:135], v[28:31]
	v_mfma_f32_16x16x32_bf16 v[24:27], v[120:123], v[136:139], v[24:27]
	v_mfma_f32_16x16x32_bf16 v[20:23], v[120:123], v[140:143], v[20:23]
	v_mfma_f32_16x16x32_bf16 v[16:19], v[120:123], v[144:147], v[16:19]
	global_load_dwordx4 v[116:119], v[40:41], off offset:704
	global_load_dwordx4 v[120:123], v[164:165], off offset:704
	ds_read_b128 v[132:135], v166 offset:49152
	ds_read_b128 v[136:139], v166 offset:49664
	ds_read_b128 v[140:143], v166 offset:50176
	ds_read_b128 v[144:147], v166 offset:50688
	s_waitcnt lgkmcnt(4)
	s_waitcnt vmcnt(7)
	v_mfma_f32_16x16x32_bf16 v[12:15], v[124:127], v[148:151], v[12:15]
	v_mfma_f32_16x16x32_bf16 v[8:11], v[124:127], v[152:155], v[8:11]
	v_mfma_f32_16x16x32_bf16 v[4:7], v[124:127], v[156:159], v[4:7]
	v_mfma_f32_16x16x32_bf16 v[0:3], v[124:127], v[160:163], v[0:3]
	s_waitcnt vmcnt(6)
	v_mfma_f32_16x16x32_bf16 v[28:31], v[128:131], v[148:151], v[28:31]
	v_mfma_f32_16x16x32_bf16 v[24:27], v[128:131], v[152:155], v[24:27]
	v_mfma_f32_16x16x32_bf16 v[20:23], v[128:131], v[156:159], v[20:23]
	v_mfma_f32_16x16x32_bf16 v[16:19], v[128:131], v[160:163], v[16:19]
	global_load_dwordx4 v[124:127], v[40:41], off offset:768
	global_load_dwordx4 v[128:131], v[164:165], off offset:768
	ds_read_b128 v[148:151], v166 offset:53248
	ds_read_b128 v[152:155], v166 offset:53760
	ds_read_b128 v[156:159], v166 offset:54272
	ds_read_b128 v[160:163], v166 offset:54784
	s_waitcnt lgkmcnt(4)
	s_waitcnt vmcnt(7)
	v_mfma_f32_16x16x32_bf16 v[12:15], v[100:103], v[132:135], v[12:15]
	v_mfma_f32_16x16x32_bf16 v[8:11], v[100:103], v[136:139], v[8:11]
	v_mfma_f32_16x16x32_bf16 v[4:7], v[100:103], v[140:143], v[4:7]
	v_mfma_f32_16x16x32_bf16 v[0:3], v[100:103], v[144:147], v[0:3]
	s_waitcnt vmcnt(6)
; #define LAS __attribute__((address_space(3)))
; __device__ __forceinline__ void ssm_stage_u(unsigned char* ws, LAS unsigned char* lds, int g, int cb, int hh, int tid) {
;     asm volatile("" : "+v"(tid));
;     const bf16* U = (const bf16*)(ws + AR_U);
;     u32x4 v[8];
; #pragma unroll
;     for (int r = 0; r < 8; ++r) { const int c = r * 512 + tid, jj = c >> 7, col = (c >> 1) & 63, part = c & 1;
;         v[r] = *(const u32x4*)(U + ((size_t)((cb * 64 + col) * 64 + hh * 32 + jj) * 512 + g * 16 + part * 8)); }
; #pragma unroll
;     for (int r = 0; r < 8; ++r) { const int c = r * 512 + tid; *(LAS u32x4*)(lds + SS_UB + c * 16) = v[r]; }
; }
; __device__ __forceinline__ void ssm_a_task(unsigned char* ws, LAS unsigned char* lds, int task, int tid) {
;     ...
;     for (int hh = 0; hh < 2; ++hh) {
;         ssm_stage_u(ws, lds, g, cb, hh, tid);
;         __syncthreads();
; #pragma unroll 4
;         for (int ks = 0; ks < 16; ++ks) {
;             bf16x8 bfr[4], afr[2];
; #pragma unroll
;             for (int a = 0; a < 2; ++a) afr[a] = *(const bf16x8*)(WA + (size_t)a * 16 * 1024 + (hh * 16 + ks) * 32);
; #pragma unroll
;             for (int c = 0; c < 4; ++c) bfr[c] = *(const LAS bf16x8*)(lds + SS_UB + (((2 * ks + (kk >> 1)) * 64 + c * 16 + rr) * 32 + (kk & 1) * 16));
; #pragma unroll
;             for (int a = 0; a < 2; ++a)
; #pragma unroll
;                 for (int c = 0; c < 4; ++c) acc[a][c] = __builtin_amdgcn_mfma_f32_16x16x32_bf16(afr[a], bfr[c], acc[a][c], 0, 0, 0);
;         }
;         __syncthreads();
	v_mfma_f32_16x16x32_bf16 v[28:31], v[104:107], v[132:135], v[28:31]
	v_mfma_f32_16x16x32_bf16 v[24:27], v[104:107], v[136:139], v[24:27]
	v_mfma_f32_16x16x32_bf16 v[20:23], v[104:107], v[140:143], v[20:23]
	v_mfma_f32_16x16x32_bf16 v[16:19], v[104:107], v[144:147], v[16:19]
	ds_read_b128 v[132:135], v166 offset:57344
	ds_read_b128 v[136:139], v166 offset:57856
	ds_read_b128 v[140:143], v166 offset:58368
	ds_read_b128 v[144:147], v166 offset:58880
	s_waitcnt lgkmcnt(4)
	s_waitcnt vmcnt(5)
	v_mfma_f32_16x16x32_bf16 v[12:15], v[108:111], v[148:151], v[12:15]
	v_mfma_f32_16x16x32_bf16 v[8:11], v[108:111], v[152:155], v[8:11]
	v_mfma_f32_16x16x32_bf16 v[4:7], v[108:111], v[156:159], v[4:7]
	v_mfma_f32_16x16x32_bf16 v[0:3], v[108:111], v[160:163], v[0:3]
	s_waitcnt vmcnt(4)
	v_mfma_f32_16x16x32_bf16 v[28:31], v[112:115], v[148:151], v[28:31]
	v_mfma_f32_16x16x32_bf16 v[24:27], v[112:115], v[152:155], v[24:27]
	v_mfma_f32_16x16x32_bf16 v[20:23], v[112:115], v[156:159], v[20:23]
	v_mfma_f32_16x16x32_bf16 v[16:19], v[112:115], v[160:163], v[16:19]
	ds_read_b128 v[148:151], v166 offset:61440
	ds_read_b128 v[152:155], v166 offset:61952
	ds_read_b128 v[156:159], v166 offset:62464
	ds_read_b128 v[160:163], v166 offset:62976
	s_waitcnt lgkmcnt(4)
	s_waitcnt vmcnt(3)
	v_mfma_f32_16x16x32_bf16 v[12:15], v[116:119], v[132:135], v[12:15]
	v_mfma_f32_16x16x32_bf16 v[8:11], v[116:119], v[136:139], v[8:11]
	v_mfma_f32_16x16x32_bf16 v[4:7], v[116:119], v[140:143], v[4:7]
	v_mfma_f32_16x16x32_bf16 v[0:3], v[116:119], v[144:147], v[0:3]
	s_waitcnt vmcnt(2)
	v_mfma_f32_16x16x32_bf16 v[28:31], v[120:123], v[132:135], v[28:31]
	v_mfma_f32_16x16x32_bf16 v[24:27], v[120:123], v[136:139], v[24:27]
	v_mfma_f32_16x16x32_bf16 v[20:23], v[120:123], v[140:143], v[20:23]
	v_mfma_f32_16x16x32_bf16 v[16:19], v[120:123], v[144:147], v[16:19]
	s_waitcnt lgkmcnt(0)
	s_waitcnt vmcnt(1)
	v_mfma_f32_16x16x32_bf16 v[12:15], v[124:127], v[148:151], v[12:15]
	v_mfma_f32_16x16x32_bf16 v[8:11], v[124:127], v[152:155], v[8:11]
	v_mfma_f32_16x16x32_bf16 v[4:7], v[124:127], v[156:159], v[4:7]
	v_mfma_f32_16x16x32_bf16 v[0:3], v[124:127], v[160:163], v[0:3]
	s_waitcnt vmcnt(0)
	v_mfma_f32_16x16x32_bf16 v[28:31], v[128:131], v[148:151], v[28:31]
	v_mfma_f32_16x16x32_bf16 v[24:27], v[128:131], v[152:155], v[24:27]
	v_mfma_f32_16x16x32_bf16 v[20:23], v[128:131], v[156:159], v[20:23]
	v_mfma_f32_16x16x32_bf16 v[16:19], v[128:131], v[160:163], v[16:19]
	s_mov_b32 s12, 0x10000
	v_mov_b32_e32 v72, v44
	s_barrier
	v_lshl_add_u64 v[38:39], v[36:37], 0, v[38:39]
	v_lshlrev_b32_e32 v40, 5, v72
	v_and_b32_e32 v40, 0xfc0, v40
	v_or3_b32 v73, s3, v40, 32
	v_lshlrev_b32_e32 v76, 4, v72
	v_ashrrev_i32_e32 v40, 7, v72
	v_add_u32_e32 v42, 0x200, v72
	v_add_u32_e32 v52, 0x400, v72
	v_add_u32_e32 v54, 0x600, v72
	v_add_u32_e32 v60, 0x800, v72
	v_add_u32_e32 v62, 0xa00, v72
	v_add_u32_e32 v70, 0xc00, v72
	v_add_u32_e32 v72, 0xe00, v72
	v_ashrrev_i32_e32 v42, 7, v42
	v_ashrrev_i32_e32 v52, 7, v52
	v_ashrrev_i32_e32 v54, 7, v54
	v_ashrrev_i32_e32 v60, 7, v60
	v_ashrrev_i32_e32 v62, 7, v62
	v_ashrrev_i32_e32 v70, 7, v70
	v_ashrrev_i32_e32 v72, 7, v72
	v_add_u32_e32 v40, v73, v40
	v_add_u32_e32 v42, v73, v42
	v_add_u32_e32 v52, v73, v52
	v_add_u32_e32 v54, v73, v54
	v_add_u32_e32 v60, v73, v60
	v_add_u32_e32 v62, v73, v62
	v_add_u32_e32 v70, v73, v70
	v_add_u32_e32 v72, v73, v72
	v_and_b32_e32 v184, 16, v76
	v_ashrrev_i32_e32 v41, 31, v40
	v_ashrrev_i32_e32 v43, 31, v42
	v_ashrrev_i32_e32 v53, 31, v52
	v_ashrrev_i32_e32 v55, 31, v54
	v_ashrrev_i32_e32 v61, 31, v60
	v_ashrrev_i32_e32 v63, 31, v62
	v_ashrrev_i32_e32 v71, 31, v70
	v_ashrrev_i32_e32 v73, 31, v72
	v_lshl_add_u64 v[68:69], s[34:35], 0, v[184:185]
	v_lshlrev_b64 v[40:41], 10, v[40:41]
	v_lshlrev_b64 v[42:43], 10, v[42:43]
	v_lshlrev_b64 v[52:53], 10, v[52:53]
	v_lshlrev_b64 v[54:55], 10, v[54:55]
	v_lshlrev_b64 v[60:61], 10, v[60:61]
	v_lshlrev_b64 v[62:63], 10, v[62:63]
	v_lshlrev_b64 v[70:71], 10, v[70:71]
	v_lshlrev_b64 v[72:73], 10, v[72:73]
	v_lshl_add_u64 v[40:41], v[68:69], 0, v[40:41]
	v_lshl_add_u64 v[48:49], v[68:69], 0, v[42:43]
	v_lshl_add_u64 v[52:53], v[68:69], 0, v[52:53]
	v_lshl_add_u64 v[56:57], v[68:69], 0, v[54:55]
	v_lshl_add_u64 v[60:61], v[68:69], 0, v[60:61]
	v_lshl_add_u64 v[64:65], v[68:69], 0, v[62:63]
	v_lshl_add_u64 v[70:71], v[68:69], 0, v[70:71]
	v_lshl_add_u64 v[72:73], v[68:69], 0, v[72:73]
	global_load_dwordx4 v[40:43], v[40:41], off
	s_nop 0
	global_load_dwordx4 v[48:51], v[48:49], off
	s_nop 0
	global_load_dwordx4 v[52:55], v[52:53], off
	s_nop 0
	global_load_dwordx4 v[56:59], v[56:57], off
	s_nop 0
	global_load_dwordx4 v[60:63], v[60:61], off
	s_nop 0
	global_load_dwordx4 v[64:67], v[64:65], off
	s_nop 0
	global_load_dwordx4 v[68:71], v[70:71], off
	s_nop 0
	global_load_dwordx4 v[72:75], v[72:73], off
	v_add_u32_e32 v76, 0, v76
	v_add_u32_e32 v76, 0x10000, v76
	s_mov_b32 s3, 0
	v_add_co_u32_e32 v164, vcc, 0xffff8000, v38
	s_nop 1
	v_addc_co_u32_e32 v165, vcc, -1, v39, vcc
	global_load_dwordx4 v[100:103], v[38:39], off offset:-192
	global_load_dwordx4 v[104:107], v[164:165], off offset:-192
	global_load_dwordx4 v[108:111], v[38:39], off offset:-128
	global_load_dwordx4 v[112:115], v[164:165], off offset:-128
	global_load_dwordx4 v[116:119], v[38:39], off offset:-64
	global_load_dwordx4 v[120:123], v[164:165], off offset:-64
	global_load_dwordx4 v[124:127], v[38:39], off offset:0
	global_load_dwordx4 v[128:131], v[164:165], off offset:0
	s_waitcnt vmcnt(15)
	ds_write_b128 v76, v[40:43]
	s_waitcnt vmcnt(14)
	ds_write_b128 v76, v[48:51] offset:8192
	s_waitcnt vmcnt(13)
	ds_write_b128 v76, v[52:55] offset:16384
	s_waitcnt vmcnt(12)
	ds_write_b128 v76, v[56:59] offset:24576
	s_waitcnt vmcnt(11)
	ds_write_b128 v76, v[60:63] offset:32768
	s_waitcnt vmcnt(10)
	ds_write_b128 v76, v[64:67] offset:40960
	s_waitcnt vmcnt(9)
	ds_write_b128 v76, v[68:71] offset:49152
	s_waitcnt vmcnt(8)
	ds_write_b128 v76, v[72:75] offset:57344
	s_waitcnt lgkmcnt(0)
	s_barrier
; #define LAS __attribute__((address_space(3)))
; __device__ __forceinline__ void ssm_a_task(unsigned char* ws, LAS unsigned char* lds, int task, int tid) {
;     ...
; #pragma unroll 4
;         for (int ks = 0; ks < 16; ++ks) {
;             bf16x8 bfr[4], afr[2];
; #pragma unroll
;             for (int a = 0; a < 2; ++a) afr[a] = *(const bf16x8*)(WA + (size_t)a * 16 * 1024 + (hh * 16 + ks) * 32);
; #pragma unroll
;             for (int c = 0; c < 4; ++c) bfr[c] = *(const LAS bf16x8*)(lds + SS_UB + (((2 * ks + (kk >> 1)) * 64 + c * 16 + rr) * 32 + (kk & 1) * 16));
; #pragma unroll
;             for (int a = 0; a < 2; ++a)
; #pragma unroll
;                 for (int c = 0; c < 4; ++c) acc[a][c] = __builtin_amdgcn_mfma_f32_16x16x32_bf16(afr[a], bfr[c], acc[a][c], 0, 0, 0);
;         }
.LBB0_606:
	v_add_u32_e32 v166, 0x10000, v47
	ds_read_b128 v[132:135], v166 offset:0
	ds_read_b128 v[136:139], v166 offset:512
	ds_read_b128 v[140:143], v166 offset:1024
	ds_read_b128 v[144:147], v166 offset:1536
	ds_read_b128 v[148:151], v166 offset:4096
	ds_read_b128 v[152:155], v166 offset:4608
	ds_read_b128 v[156:159], v166 offset:5120
	ds_read_b128 v[160:163], v166 offset:5632
	s_waitcnt lgkmcnt(4)
	s_waitcnt vmcnt(7)
	v_mfma_f32_16x16x32_bf16 v[12:15], v[100:103], v[132:135], v[12:15]
	v_mfma_f32_16x16x32_bf16 v[8:11], v[100:103], v[136:139], v[8:11]
	v_mfma_f32_16x16x32_bf16 v[4:7], v[100:103], v[140:143], v[4:7]
	v_mfma_f32_16x16x32_bf16 v[0:3], v[100:103], v[144:147], v[0:3]
	s_waitcnt vmcnt(6)
	v_mfma_f32_16x16x32_bf16 v[28:31], v[104:107], v[132:135], v[28:31]
	v_mfma_f32_16x16x32_bf16 v[24:27], v[104:107], v[136:139], v[24:27]
	v_mfma_f32_16x16x32_bf16 v[20:23], v[104:107], v[140:143], v[20:23]
	v_mfma_f32_16x16x32_bf16 v[16:19], v[104:107], v[144:147], v[16:19]
	global_load_dwordx4 v[100:103], v[38:39], off offset:64
	global_load_dwordx4 v[104:107], v[164:165], off offset:64
	ds_read_b128 v[132:135], v166 offset:8192
	ds_read_b128 v[136:139], v166 offset:8704
	ds_read_b128 v[140:143], v166 offset:9216
	ds_read_b128 v[144:147], v166 offset:9728
	s_waitcnt lgkmcnt(4)
	s_waitcnt vmcnt(7)
	v_mfma_f32_16x16x32_bf16 v[12:15], v[108:111], v[148:151], v[12:15]
	v_mfma_f32_16x16x32_bf16 v[8:11], v[108:111], v[152:155], v[8:11]
	v_mfma_f32_16x16x32_bf16 v[4:7], v[108:111], v[156:159], v[4:7]
	v_mfma_f32_16x16x32_bf16 v[0:3], v[108:111], v[160:163], v[0:3]
	s_waitcnt vmcnt(6)
	v_mfma_f32_16x16x32_bf16 v[28:31], v[112:115], v[148:151], v[28:31]
	v_mfma_f32_16x16x32_bf16 v[24:27], v[112:115], v[152:155], v[24:27]
	v_mfma_f32_16x16x32_bf16 v[20:23], v[112:115], v[156:159], v[20:23]
	v_mfma_f32_16x16x32_bf16 v[16:19], v[112:115], v[160:163], v[16:19]
	global_load_dwordx4 v[108:111], v[38:39], off offset:128
	global_load_dwordx4 v[112:115], v[164:165], off offset:128
	ds_read_b128 v[148:151], v166 offset:12288
	ds_read_b128 v[152:155], v166 offset:12800
	ds_read_b128 v[156:159], v166 offset:13312
	ds_read_b128 v[160:163], v166 offset:13824
	s_waitcnt lgkmcnt(4)
	s_waitcnt vmcnt(7)
	v_mfma_f32_16x16x32_bf16 v[12:15], v[116:119], v[132:135], v[12:15]
	v_mfma_f32_16x16x32_bf16 v[8:11], v[116:119], v[136:139], v[8:11]
	v_mfma_f32_16x16x32_bf16 v[4:7], v[116:119], v[140:143], v[4:7]
	v_mfma_f32_16x16x32_bf16 v[0:3], v[116:119], v[144:147], v[0:3]
	s_waitcnt vmcnt(6)
	v_mfma_f32_16x16x32_bf16 v[28:31], v[120:123], v[132:135], v[28:31]
	v_mfma_f32_16x16x32_bf16 v[24:27], v[120:123], v[136:139], v[24:27]
	v_mfma_f32_16x16x32_bf16 v[20:23], v[120:123], v[140:143], v[20:23]
	v_mfma_f32_16x16x32_bf16 v[16:19], v[120:123], v[144:147], v[16:19]
	global_load_dwordx4 v[116:119], v[38:39], off offset:192
	global_load_dwordx4 v[120:123], v[164:165], off offset:192
	ds_read_b128 v[132:135], v166 offset:16384
	ds_read_b128 v[136:139], v166 offset:16896
	ds_read_b128 v[140:143], v166 offset:17408
	ds_read_b128 v[144:147], v166 offset:17920
	s_waitcnt lgkmcnt(4)
	s_waitcnt vmcnt(7)
	v_mfma_f32_16x16x32_bf16 v[12:15], v[124:127], v[148:151], v[12:15]
	v_mfma_f32_16x16x32_bf16 v[8:11], v[124:127], v[152:155], v[8:11]
	v_mfma_f32_16x16x32_bf16 v[4:7], v[124:127], v[156:159], v[4:7]
	v_mfma_f32_16x16x32_bf16 v[0:3], v[124:127], v[160:163], v[0:3]
	s_waitcnt vmcnt(6)
	v_mfma_f32_16x16x32_bf16 v[28:31], v[128:131], v[148:151], v[28:31]
	v_mfma_f32_16x16x32_bf16 v[24:27], v[128:131], v[152:155], v[24:27]
	v_mfma_f32_16x16x32_bf16 v[20:23], v[128:131], v[156:159], v[20:23]
	v_mfma_f32_16x16x32_bf16 v[16:19], v[128:131], v[160:163], v[16:19]
	global_load_dwordx4 v[124:127], v[38:39], off offset:256
	global_load_dwordx4 v[128:131], v[164:165], off offset:256
	ds_read_b128 v[148:151], v166 offset:20480
	ds_read_b128 v[152:155], v166 offset:20992
	ds_read_b128 v[156:159], v166 offset:21504
	ds_read_b128 v[160:163], v166 offset:22016
	s_waitcnt lgkmcnt(4)
	s_waitcnt vmcnt(7)
	v_mfma_f32_16x16x32_bf16 v[12:15], v[100:103], v[132:135], v[12:15]
	v_mfma_f32_16x16x32_bf16 v[8:11], v[100:103], v[136:139], v[8:11]
	v_mfma_f32_16x16x32_bf16 v[4:7], v[100:103], v[140:143], v[4:7]
	v_mfma_f32_16x16x32_bf16 v[0:3], v[100:103], v[144:147], v[0:3]
	s_waitcnt vmcnt(6)
	v_mfma_f32_16x16x32_bf16 v[28:31], v[104:107], v[132:135], v[28:31]
	v_mfma_f32_16x16x32_bf16 v[24:27], v[104:107], v[136:139], v[24:27]
	v_mfma_f32_16x16x32_bf16 v[20:23], v[104:107], v[140:143], v[20:23]
	v_mfma_f32_16x16x32_bf16 v[16:19], v[104:107], v[144:147], v[16:19]
	global_load_dwordx4 v[100:103], v[38:39], off offset:320
	global_load_dwordx4 v[104:107], v[164:165], off offset:320
	ds_read_b128 v[132:135], v166 offset:24576
	ds_read_b128 v[136:139], v166 offset:25088
	ds_read_b128 v[140:143], v166 offset:25600
	ds_read_b128 v[144:147], v166 offset:26112
	s_waitcnt lgkmcnt(4)
	s_waitcnt vmcnt(7)
	v_mfma_f32_16x16x32_bf16 v[12:15], v[108:111], v[148:151], v[12:15]
	v_mfma_f32_16x16x32_bf16 v[8:11], v[108:111], v[152:155], v[8:11]
	v_mfma_f32_16x16x32_bf16 v[4:7], v[108:111], v[156:159], v[4:7]
	v_mfma_f32_16x16x32_bf16 v[0:3], v[108:111], v[160:163], v[0:3]
	s_waitcnt vmcnt(6)
	v_mfma_f32_16x16x32_bf16 v[28:31], v[112:115], v[148:151], v[28:31]
	v_mfma_f32_16x16x32_bf16 v[24:27], v[112:115], v[152:155], v[24:27]
	v_mfma_f32_16x16x32_bf16 v[20:23], v[112:115], v[156:159], v[20:23]
	v_mfma_f32_16x16x32_bf16 v[16:19], v[112:115], v[160:163], v[16:19]
	global_load_dwordx4 v[108:111], v[38:39], off offset:384
	global_load_dwordx4 v[112:115], v[164:165], off offset:384
	ds_read_b128 v[148:151], v166 offset:28672
	ds_read_b128 v[152:155], v166 offset:29184
	ds_read_b128 v[156:159], v166 offset:29696
	ds_read_b128 v[160:163], v166 offset:30208
	s_waitcnt lgkmcnt(4)
; #define LAS __attribute__((address_space(3)))
; __device__ __forceinline__ void ssm_a_task(unsigned char* ws, LAS unsigned char* lds, int task, int tid) {
;     ...
; #pragma unroll 4
;         for (int ks = 0; ks < 16; ++ks) {
;             bf16x8 bfr[4], afr[2];
; #pragma unroll
;             for (int a = 0; a < 2; ++a) afr[a] = *(const bf16x8*)(WA + (size_t)a * 16 * 1024 + (hh * 16 + ks) * 32);
; #pragma unroll
;             for (int c = 0; c < 4; ++c) bfr[c] = *(const LAS bf16x8*)(lds + SS_UB + (((2 * ks + (kk >> 1)) * 64 + c * 16 + rr) * 32 + (kk & 1) * 16));
; #pragma unroll
;             for (int a = 0; a < 2; ++a)
; #pragma unroll
;                 for (int c = 0; c < 4; ++c) acc[a][c] = __builtin_amdgcn_mfma_f32_16x16x32_bf16(afr[a], bfr[c], acc[a][c], 0, 0, 0);
;         }
	s_waitcnt vmcnt(7)
	v_mfma_f32_16x16x32_bf16 v[12:15], v[116:119], v[132:135], v[12:15]
	v_mfma_f32_16x16x32_bf16 v[8:11], v[116:119], v[136:139], v[8:11]
	v_mfma_f32_16x16x32_bf16 v[4:7], v[116:119], v[140:143], v[4:7]
	v_mfma_f32_16x16x32_bf16 v[0:3], v[116:119], v[144:147], v[0:3]
	s_waitcnt vmcnt(6)
	v_mfma_f32_16x16x32_bf16 v[28:31], v[120:123], v[132:135], v[28:31]
	v_mfma_f32_16x16x32_bf16 v[24:27], v[120:123], v[136:139], v[24:27]
	v_mfma_f32_16x16x32_bf16 v[20:23], v[120:123], v[140:143], v[20:23]
	v_mfma_f32_16x16x32_bf16 v[16:19], v[120:123], v[144:147], v[16:19]
	global_load_dwordx4 v[116:119], v[38:39], off offset:448
	global_load_dwordx4 v[120:123], v[164:165], off offset:448
	ds_read_b128 v[132:135], v166 offset:32768
	ds_read_b128 v[136:139], v166 offset:33280
	ds_read_b128 v[140:143], v166 offset:33792
	ds_read_b128 v[144:147], v166 offset:34304
	s_waitcnt lgkmcnt(4)
	s_waitcnt vmcnt(7)
	v_mfma_f32_16x16x32_bf16 v[12:15], v[124:127], v[148:151], v[12:15]
	v_mfma_f32_16x16x32_bf16 v[8:11], v[124:127], v[152:155], v[8:11]
	v_mfma_f32_16x16x32_bf16 v[4:7], v[124:127], v[156:159], v[4:7]
	v_mfma_f32_16x16x32_bf16 v[0:3], v[124:127], v[160:163], v[0:3]
	s_waitcnt vmcnt(6)
	v_mfma_f32_16x16x32_bf16 v[28:31], v[128:131], v[148:151], v[28:31]
	v_mfma_f32_16x16x32_bf16 v[24:27], v[128:131], v[152:155], v[24:27]
	v_mfma_f32_16x16x32_bf16 v[20:23], v[128:131], v[156:159], v[20:23]
	v_mfma_f32_16x16x32_bf16 v[16:19], v[128:131], v[160:163], v[16:19]
	global_load_dwordx4 v[124:127], v[38:39], off offset:512
	global_load_dwordx4 v[128:131], v[164:165], off offset:512
	ds_read_b128 v[148:151], v166 offset:36864
	ds_read_b128 v[152:155], v166 offset:37376
	ds_read_b128 v[156:159], v166 offset:37888
	ds_read_b128 v[160:163], v166 offset:38400
	s_waitcnt lgkmcnt(4)
	s_waitcnt vmcnt(7)
	v_mfma_f32_16x16x32_bf16 v[12:15], v[100:103], v[132:135], v[12:15]
	v_mfma_f32_16x16x32_bf16 v[8:11], v[100:103], v[136:139], v[8:11]
	v_mfma_f32_16x16x32_bf16 v[4:7], v[100:103], v[140:143], v[4:7]
	v_mfma_f32_16x16x32_bf16 v[0:3], v[100:103], v[144:147], v[0:3]
	s_waitcnt vmcnt(6)
	v_mfma_f32_16x16x32_bf16 v[28:31], v[104:107], v[132:135], v[28:31]
	v_mfma_f32_16x16x32_bf16 v[24:27], v[104:107], v[136:139], v[24:27]
	v_mfma_f32_16x16x32_bf16 v[20:23], v[104:107], v[140:143], v[20:23]
	v_mfma_f32_16x16x32_bf16 v[16:19], v[104:107], v[144:147], v[16:19]
	global_load_dwordx4 v[100:103], v[38:39], off offset:576
	global_load_dwordx4 v[104:107], v[164:165], off offset:576
	ds_read_b128 v[132:135], v166 offset:40960
	ds_read_b128 v[136:139], v166 offset:41472
	ds_read_b128 v[140:143], v166 offset:41984
	ds_read_b128 v[144:147], v166 offset:42496
	s_waitcnt lgkmcnt(4)
	s_waitcnt vmcnt(7)
	v_mfma_f32_16x16x32_bf16 v[12:15], v[108:111], v[148:151], v[12:15]
	v_mfma_f32_16x16x32_bf16 v[8:11], v[108:111], v[152:155], v[8:11]
	v_mfma_f32_16x16x32_bf16 v[4:7], v[108:111], v[156:159], v[4:7]
	v_mfma_f32_16x16x32_bf16 v[0:3], v[108:111], v[160:163], v[0:3]
	s_waitcnt vmcnt(6)
	v_mfma_f32_16x16x32_bf16 v[28:31], v[112:115], v[148:151], v[28:31]
	v_mfma_f32_16x16x32_bf16 v[24:27], v[112:115], v[152:155], v[24:27]
	v_mfma_f32_16x16x32_bf16 v[20:23], v[112:115], v[156:159], v[20:23]
	v_mfma_f32_16x16x32_bf16 v[16:19], v[112:115], v[160:163], v[16:19]
	global_load_dwordx4 v[108:111], v[38:39], off offset:640
	global_load_dwordx4 v[112:115], v[164:165], off offset:640
	ds_read_b128 v[148:151], v166 offset:45056
	ds_read_b128 v[152:155], v166 offset:45568
	ds_read_b128 v[156:159], v166 offset:46080
	ds_read_b128 v[160:163], v166 offset:46592
	s_waitcnt lgkmcnt(4)
	s_waitcnt vmcnt(7)
	v_mfma_f32_16x16x32_bf16 v[12:15], v[116:119], v[132:135], v[12:15]
	v_mfma_f32_16x16x32_bf16 v[8:11], v[116:119], v[136:139], v[8:11]
	v_mfma_f32_16x16x32_bf16 v[4:7], v[116:119], v[140:143], v[4:7]
	v_mfma_f32_16x16x32_bf16 v[0:3], v[116:119], v[144:147], v[0:3]
	s_waitcnt vmcnt(6)
	v_mfma_f32_16x16x32_bf16 v[28:31], v[120:123], v[132:135], v[28:31]
	v_mfma_f32_16x16x32_bf16 v[24:27], v[120:123], v[136:139], v[24:27]
	v_mfma_f32_16x16x32_bf16 v[20:23], v[120:123], v[140:143], v[20:23]
	v_mfma_f32_16x16x32_bf16 v[16:19], v[120:123], v[144:147], v[16:19]
	global_load_dwordx4 v[116:119], v[38:39], off offset:704
	global_load_dwordx4 v[120:123], v[164:165], off offset:704
	ds_read_b128 v[132:135], v166 offset:49152
	ds_read_b128 v[136:139], v166 offset:49664
	ds_read_b128 v[140:143], v166 offset:50176
	ds_read_b128 v[144:147], v166 offset:50688
	s_waitcnt lgkmcnt(4)
	s_waitcnt vmcnt(7)
; #define LAS __attribute__((address_space(3)))
; __device__ __forceinline__ void ssm_a_task(unsigned char* ws, LAS unsigned char* lds, int task, int tid) {
;     ...
; #pragma unroll 4
;         for (int ks = 0; ks < 16; ++ks) {
;             bf16x8 bfr[4], afr[2];
; #pragma unroll
;             for (int a = 0; a < 2; ++a) afr[a] = *(const bf16x8*)(WA + (size_t)a * 16 * 1024 + (hh * 16 + ks) * 32);
; #pragma unroll
;             for (int c = 0; c < 4; ++c) bfr[c] = *(const LAS bf16x8*)(lds + SS_UB + (((2 * ks + (kk >> 1)) * 64 + c * 16 + rr) * 32 + (kk & 1) * 16));
; #pragma unroll
;             for (int a = 0; a < 2; ++a)
; #pragma unroll
;                 for (int c = 0; c < 4; ++c) acc[a][c] = __builtin_amdgcn_mfma_f32_16x16x32_bf16(afr[a], bfr[c], acc[a][c], 0, 0, 0);
;         }
;         __syncthreads();
;     }
;     float* S = (float*)(ws + AR_S);
; #pragma unroll
;     for (int a = 0; a < 2; ++a)
; #pragma unroll
;         for (int c = 0; c < 4; ++c) { const int col = cb * 64 + c * 16 + rr; *(f32x4*)(S + ((size_t)(col * NG + g) * 256 + wid * 32 + a * 16 + 4 * kk)) = acc[a][c]; }
	v_mfma_f32_16x16x32_bf16 v[12:15], v[124:127], v[148:151], v[12:15]
	v_mfma_f32_16x16x32_bf16 v[8:11], v[124:127], v[152:155], v[8:11]
	v_mfma_f32_16x16x32_bf16 v[4:7], v[124:127], v[156:159], v[4:7]
	v_mfma_f32_16x16x32_bf16 v[0:3], v[124:127], v[160:163], v[0:3]
	s_waitcnt vmcnt(6)
	v_mfma_f32_16x16x32_bf16 v[28:31], v[128:131], v[148:151], v[28:31]
	v_mfma_f32_16x16x32_bf16 v[24:27], v[128:131], v[152:155], v[24:27]
	v_mfma_f32_16x16x32_bf16 v[20:23], v[128:131], v[156:159], v[20:23]
	v_mfma_f32_16x16x32_bf16 v[16:19], v[128:131], v[160:163], v[16:19]
	global_load_dwordx4 v[124:127], v[38:39], off offset:768
	global_load_dwordx4 v[128:131], v[164:165], off offset:768
	ds_read_b128 v[148:151], v166 offset:53248
	ds_read_b128 v[152:155], v166 offset:53760
	ds_read_b128 v[156:159], v166 offset:54272
	ds_read_b128 v[160:163], v166 offset:54784
	s_waitcnt lgkmcnt(4)
	s_waitcnt vmcnt(7)
	v_mfma_f32_16x16x32_bf16 v[12:15], v[100:103], v[132:135], v[12:15]
	v_mfma_f32_16x16x32_bf16 v[8:11], v[100:103], v[136:139], v[8:11]
	v_mfma_f32_16x16x32_bf16 v[4:7], v[100:103], v[140:143], v[4:7]
	v_mfma_f32_16x16x32_bf16 v[0:3], v[100:103], v[144:147], v[0:3]
	s_waitcnt vmcnt(6)
	v_mfma_f32_16x16x32_bf16 v[28:31], v[104:107], v[132:135], v[28:31]
	v_mfma_f32_16x16x32_bf16 v[24:27], v[104:107], v[136:139], v[24:27]
	v_mfma_f32_16x16x32_bf16 v[20:23], v[104:107], v[140:143], v[20:23]
	v_mfma_f32_16x16x32_bf16 v[16:19], v[104:107], v[144:147], v[16:19]
	ds_read_b128 v[132:135], v166 offset:57344
	ds_read_b128 v[136:139], v166 offset:57856
	ds_read_b128 v[140:143], v166 offset:58368
	ds_read_b128 v[144:147], v166 offset:58880
	s_waitcnt lgkmcnt(4)
	s_waitcnt vmcnt(5)
	v_mfma_f32_16x16x32_bf16 v[12:15], v[108:111], v[148:151], v[12:15]
	v_mfma_f32_16x16x32_bf16 v[8:11], v[108:111], v[152:155], v[8:11]
	v_mfma_f32_16x16x32_bf16 v[4:7], v[108:111], v[156:159], v[4:7]
	v_mfma_f32_16x16x32_bf16 v[0:3], v[108:111], v[160:163], v[0:3]
	s_waitcnt vmcnt(4)
	v_mfma_f32_16x16x32_bf16 v[28:31], v[112:115], v[148:151], v[28:31]
	v_mfma_f32_16x16x32_bf16 v[24:27], v[112:115], v[152:155], v[24:27]
	v_mfma_f32_16x16x32_bf16 v[20:23], v[112:115], v[156:159], v[20:23]
	v_mfma_f32_16x16x32_bf16 v[16:19], v[112:115], v[160:163], v[16:19]
	ds_read_b128 v[148:151], v166 offset:61440
	ds_read_b128 v[152:155], v166 offset:61952
	ds_read_b128 v[156:159], v166 offset:62464
	ds_read_b128 v[160:163], v166 offset:62976
	s_waitcnt lgkmcnt(4)
	s_waitcnt vmcnt(3)
	v_mfma_f32_16x16x32_bf16 v[12:15], v[116:119], v[132:135], v[12:15]
	v_mfma_f32_16x16x32_bf16 v[8:11], v[116:119], v[136:139], v[8:11]
	v_mfma_f32_16x16x32_bf16 v[4:7], v[116:119], v[140:143], v[4:7]
	v_mfma_f32_16x16x32_bf16 v[0:3], v[116:119], v[144:147], v[0:3]
	s_waitcnt vmcnt(2)
	v_mfma_f32_16x16x32_bf16 v[28:31], v[120:123], v[132:135], v[28:31]
	v_mfma_f32_16x16x32_bf16 v[24:27], v[120:123], v[136:139], v[24:27]
	v_mfma_f32_16x16x32_bf16 v[20:23], v[120:123], v[140:143], v[20:23]
	v_mfma_f32_16x16x32_bf16 v[16:19], v[120:123], v[144:147], v[16:19]
	s_waitcnt lgkmcnt(0)
	s_waitcnt vmcnt(1)
	v_mfma_f32_16x16x32_bf16 v[12:15], v[124:127], v[148:151], v[12:15]
	v_mfma_f32_16x16x32_bf16 v[8:11], v[124:127], v[152:155], v[8:11]
	v_mfma_f32_16x16x32_bf16 v[4:7], v[124:127], v[156:159], v[4:7]
	v_mfma_f32_16x16x32_bf16 v[0:3], v[124:127], v[160:163], v[0:3]
	s_waitcnt vmcnt(0)
	v_mfma_f32_16x16x32_bf16 v[28:31], v[128:131], v[148:151], v[28:31]
	v_mfma_f32_16x16x32_bf16 v[24:27], v[128:131], v[152:155], v[24:27]
	v_mfma_f32_16x16x32_bf16 v[20:23], v[128:131], v[156:159], v[20:23]
	v_mfma_f32_16x16x32_bf16 v[16:19], v[128:131], v[160:163], v[16:19]
	s_mov_b32 s3, 0x10000
	v_lshl_or_b32 v38, s17, 11, v45
	v_add_u32_e32 v38, s16, v38
	v_ashrrev_i32_e32 v39, 31, v38
	v_lshlrev_b64 v[40:41], 10, v[38:39]
	v_lshl_add_u64 v[40:41], v[32:33], 0, v[40:41]
	s_barrier
	global_store_dwordx4 v[40:41], v[28:31], off
	s_add_i32 s54, s54, s76
	s_cmpk_gt_i32 s54, 0xff
	v_add_u32_e32 v28, 0x200, v38
	v_ashrrev_i32_e32 v29, 31, v28
	v_lshlrev_b64 v[28:29], 10, v[28:29]
	v_lshl_add_u64 v[28:29], v[32:33], 0, v[28:29]
	global_store_dwordx4 v[28:29], v[24:27], off
	s_nop 1
	v_add_u32_e32 v24, 0x400, v38
	v_ashrrev_i32_e32 v25, 31, v24
	v_lshlrev_b64 v[24:25], 10, v[24:25]
	v_lshl_add_u64 v[24:25], v[32:33], 0, v[24:25]
	global_store_dwordx4 v[24:25], v[20:23], off
	s_nop 1
	v_add_u32_e32 v20, 0x600, v38
	v_ashrrev_i32_e32 v21, 31, v20
	v_lshlrev_b64 v[20:21], 10, v[20:21]
	v_lshl_add_u64 v[20:21], v[32:33], 0, v[20:21]
	global_store_dwordx4 v[20:21], v[16:19], off
	global_store_dwordx4 v[40:41], v[12:15], off offset:64
	global_store_dwordx4 v[28:29], v[8:11], off offset:64
	global_store_dwordx4 v[24:25], v[4:7], off offset:64
	global_store_dwordx4 v[20:21], v[0:3], off offset:64
	s_cbranch_scc0 .LBB0_603
